# v91 with the kernel body shifted by 8 bytes (two s_nop at entry): code-placement variant
# baseline (speedup 1.0000x reference)
_Z6mk_fwd4Args:
	s_nop 0
	s_nop 0
	s_mov_b64 s[78:79], s[0:1]
	s_load_dwordx2 s[0:1], s[78:79], 0xbc
	v_and_b32_e32 v234, 0x3ff, v0
	v_cmp_gt_u32_e32 vcc, 2, v234
	s_waitcnt lgkmcnt(0)
	v_writelane_b32 v252, s0, 0
	s_nop 1
	v_writelane_b32 v252, s1, 1
	s_add_u32 s0, s78, 0xc0
	s_addc_u32 s1, s79, 0
	v_writelane_b32 v252, s0, 2
	s_nop 1
	v_writelane_b32 v252, s1, 3
	s_and_saveexec_b64 s[0:1], vcc
	v_lshl_add_u32 v1, v234, 2, 0
	v_add_u32_e32 v1, 0x23000, v1
	v_mov_b32_e32 v2, 0
	ds_write_b32 v1, v2
	s_or_b64 exec, exec, s[0:1]
	s_waitcnt lgkmcnt(0)
	s_barrier
	s_load_dwordx2 s[16:17], s[78:79], 0xb0
	s_getreg_b32 s0, hwreg(HW_REG_XCC_ID, 0, 4)
	s_and_b32 s3, s0, 15
	v_cmp_eq_u32_e64 s[4:5], 0, v234
	s_mov_b64 s[0:1], exec
	s_nop 0
	v_writelane_b32 v252, s4, 4
	s_nop 1
	v_writelane_b32 v252, s5, 5
	s_waitcnt lgkmcnt(0)
	v_writelane_b32 v252, s16, 6
	s_and_b64 s[4:5], s[0:1], s[4:5]
	s_nop 0
	v_writelane_b32 v252, s17, 7
	s_mov_b64 exec, s[4:5]
	s_cbranch_execz .LBB0_14
	s_mov_b64 s[6:7], exec
	v_mbcnt_lo_u32_b32 v1, s6, 0
	v_mbcnt_hi_u32_b32 v1, s7, v1
	v_cmp_eq_u32_e32 vcc, 0, v1
	s_and_saveexec_b64 s[4:5], vcc
	s_cbranch_execz .LBB0_5
	s_lshl_b32 s8, s3, 8
	s_bcnt1_i32_b64 s6, s[6:7]
	v_mov_b32_e32 v1, s8
	v_mov_b32_e32 v2, s6
	global_atomic_add v1, v2, s[16:17] offset:1024
